# out-proj layer 0: CUs that own only 2 tiles start half a tile period late so their epilogue HBM bursts fall into the other CUs' main loops
# baseline (speedup 1.0000x reference)
; DI int tidx() { int t = threadIdx.x; asm volatile("" : "+v"(t)); return t; }
; template <int EPI>
; DI bool tile_coords(int j, int mpx, int& m0, int& n0) {
;     ...
;   } else {
;     if (q >= mpx * 4) return false;
;     m0 = (x * mpx + (q >> 2)) * 256;
;     n0 = (q & 3) * 256;
;   }
;   return true;
; }
; template <int EPI>
; DI void gemm_phase(const P& p, int l, const u16* __restrict__ A, const u16* __restrict__ Bt, int mpx, char* lds) {
;   const int tid = tidx();
;   int t = 0;
;   int m0, n0;
;   if (!tile_coords<EPI>(t, mpx, m0, n0)) return;
;   const unsigned voffb = (unsigned)(((tid >> 3) * 1024 + (tid & 7) * 8) * 2);
;   const u16* Ag = A + (size_t)m0 * 1024;
;   const u16* Bg = Bt + (size_t)n0 * 1024;
;   uint4 ra0, ra1, ra2, ra3, rb0, rb1, rb2, rb3;
;     ...
;   GLOAD(Ag, Bg, 0)
;   u16* As0 = (u16*)lds;
;   u16* Bs0 = As0 + 256 * 64;
;   u16* As1 = Bs0 + 256 * 64;
;   u16* Bs1 = As1 + 256 * 64;
;   const int lw = (tid >> 3) * 64 + (((tid & 7) ^ ((tid >> 3) & 7)) * 8);
;   GSTORE(As0, Bs0)
.LBB0_66:
	s_andn2_b64 vcc, exec, s[0:1]
	s_cbranch_vccnz .LBB0_73
	s_cmp_lt_u32 s23, 4
	s_cselect_b64 s[0:1], -1, 0
	s_and_b64 s[26:27], s[0:1], exec
	s_cselect_b32 s2, 18, 16
	s_lshl_b32 s25, s2, 2
	s_cmp_lt_u32 s84, s25
	v_mov_b32_e32 v0, v195
	s_cbranch_scc0 .LBB0_73
	s_cmp_lg_u32 s50, 0
	s_cbranch_scc1 .Ldesync_out_skip
	s_cmp_lt_u32 s84, 8
	s_cbranch_scc1 .Ldesync_out_skip
	s_sleep 127
	s_sleep 127
	s_sleep 127
	s_sleep 127
.Ldesync_out_skip:
	s_ashr_i32 s51, s50, 31
	s_lshl_b64 s[26:27], s[50:51], 21
	s_add_u32 s26, s14, s26
	v_readlane_b32 s40, v254, 11
	s_addc_u32 s27, s15, s27
	s_mul_i32 s51, s2, s40
	v_readlane_b32 s2, v254, 8
	s_add_u32 s46, s26, s2
	v_readlane_b32 s2, v254, 6
	s_addc_u32 s47, s27, 0
	s_add_i32 s2, s51, s2
	s_lshl_b32 s2, s2, 8
	s_lshl_b64 s[40:41], s[2:3], 11
	v_lshlrev_b32_e32 v2, 4, v0
	s_add_u32 s48, s16, s40
	v_ashrrev_i32_e32 v34, 3, v0
	v_and_b32_e32 v2, 0x70, v2
	s_addc_u32 s49, s17, s41
	v_lshl_or_b32 v196, v34, 11, v2
	v_mov_b32_e32 v197, v1
	v_lshl_add_u64 v[14:15], s[48:49], 0, v[196:197]
	v_add_co_u32_e32 v6, vcc, s33, v14
	global_load_dwordx4 v[2:5], v196, s[48:49]
	global_load_dwordx4 v[18:21], v196, s[46:47]
	v_addc_co_u32_e32 v7, vcc, 0, v15, vcc
	v_add_co_u32_e32 v10, vcc, s35, v14
	v_lshl_add_u64 v[30:31], s[46:47], 0, v[196:197]
	s_nop 0
	v_addc_co_u32_e32 v11, vcc, 0, v15, vcc
	v_add_co_u32_e32 v14, vcc, s39, v14
	global_load_dwordx4 v[6:9], v[6:7], off
	s_nop 0
	v_addc_co_u32_e32 v15, vcc, 0, v15, vcc
	v_add_co_u32_e32 v22, vcc, s33, v30
	global_load_dwordx4 v[10:13], v[10:11], off
	s_nop 0
	v_addc_co_u32_e32 v23, vcc, 0, v31, vcc
	global_load_dwordx4 v[14:17], v[14:15], off
	v_add_co_u32_e32 v26, vcc, s35, v30
	global_load_dwordx4 v[22:25], v[22:23], off
	s_nop 0
	v_addc_co_u32_e32 v27, vcc, 0, v31, vcc
	v_add_co_u32_e32 v30, vcc, s39, v30
	global_load_dwordx4 v[26:29], v[26:27], off
	s_nop 0
	v_addc_co_u32_e32 v31, vcc, 0, v31, vcc
	global_load_dwordx4 v[30:33], v[30:31], off
	v_xor_b32_e32 v35, v34, v0
	s_load_dword s40, s[76:77], 0x0
	v_lshlrev_b32_e32 v35, 4, v35
	v_and_b32_e32 v35, 0x70, v35
	v_lshl_or_b32 v34, v34, 7, v35
	v_add_u32_e32 v198, 32, v34
	s_waitcnt lgkmcnt(0)
	s_lshr_b32 s57, s40, 3
	v_readlane_b32 s40, v255, 23
	s_mov_b32 s56, 0
	v_add_u32_e32 v199, s78, v34
	v_add_u32_e32 v203, s40, v34
	s_mov_b32 s60, s2
	v_readlane_b32 s61, v254, 7
	s_waitcnt vmcnt(7)
	ds_write_b128 v198, v[2:5]
	s_waitcnt vmcnt(5)
	ds_write_b128 v198, v[6:9] offset:8192
	s_waitcnt vmcnt(4)
	ds_write_b128 v198, v[10:13] offset:16384
	s_waitcnt vmcnt(3)
	ds_write_b128 v198, v[14:17] offset:24576
	ds_write_b128 v198, v[18:21] offset:32768
	s_waitcnt vmcnt(2)
	ds_write_b128 v198, v[22:25] offset:40960
	s_waitcnt vmcnt(1)
	ds_write_b128 v198, v[26:29] offset:49152
	s_waitcnt vmcnt(0)
	ds_write_b128 v198, v[30:33] offset:57344
	v_lshrrev_b32_e32 v2, 4, v0
	v_bfe_u32 v3, v0, 4, 2
	v_and_b32_e32 v4, 7, v0
	v_bitop3_b32 v2, v2, v4, 3 bitop3:0x6c
	v_add_u32_e32 v6, 0x2000, v34
	v_bitop3_b32 v3, v3, v4, 4 bitop3:0x36
	v_lshlrev_b32_e32 v2, 4, v2
	v_add_u32_e32 v200, s78, v6
	v_add_u32_e32 v7, 0x4000, v34
	v_add_u32_e32 v204, s40, v6
	v_lshlrev_b32_e32 v3, 4, v3
	v_lshlrev_b32_e32 v6, 7, v0
	v_lshlrev_b32_e32 v0, 6, v0
	v_add_u32_e32 v5, 32, v2
	v_add_u32_e32 v201, s78, v7
	v_add_u32_e32 v8, 0x6000, v34
	v_add_u32_e32 v205, s40, v7
	v_add_u32_e32 v4, 32, v3
	v_and_b32_e32 v7, 0x6000, v6
	v_and_b32_e32 v0, 0xffffc000, v0
	v_add_u32_e32 v202, s78, v8
	v_add_u32_e32 v206, s40, v8
	v_and_b32_e32 v6, 0x780, v6
	v_add_u32_e32 v8, v5, v7
	v_add_u32_e32 v5, v5, v0
	v_add_u32_e32 v9, v4, v7
	v_add_u32_e32 v4, v4, v0
	v_add3_u32 v10, s40, v2, v7
	v_add3_u32 v2, s78, v2, v0
	v_add3_u32 v7, s40, v3, v7
	v_add3_u32 v0, s78, v3, v0
	v_add_u32_e32 v207, v8, v6
	v_add_u32_e32 v227, v5, v6
	v_add_u32_e32 v228, v9, v6
	v_add_u32_e32 v229, v4, v6
	v_add_u32_e32 v230, v10, v6
	v_add_u32_e32 v231, v2, v6
	v_add_u32_e32 v232, v7, v6
	v_add_u32_e32 v233, v0, v6
